# attention prologue: the two dependent work-queue atomics merged into one atomic add of 2 (second item = first + 1); on top of the previous best
# speedup vs baseline: 1.0105x; 1.0007x over previous
; DI void phase_attn(const Params& P, int l, LAS unsigned char* lds) {
;     ...
;     if (tid == 0) { const int a0 = (int)__hip_atomic_fetch_add(qctr, 1u, __ATOMIC_RELAXED, __HIP_MEMORY_SCOPE_AGENT); const int a1 = (int)__hip_atomic_fetch_add(qctr, 1u, __ATOMIC_RELAXED, __HIP_MEMORY_SCOPE_AGENT); slot[0] = a0; slot[1] = a1; }
.LBB0_463:
	s_add_u32 s2, s50, 0x29e6f800
	s_addc_u32 s3, s51, 0
	v_cmp_eq_u32_e64 s[0:1], 0, v137
	s_and_saveexec_b64 s[4:5], s[0:1]
	s_cbranch_execz .LBB0_469
	s_mov_b64 s[10:11], exec
	v_mbcnt_lo_u32_b32 v3, s10, 0
	v_mbcnt_hi_u32_b32 v3, s11, v3
	v_cmp_eq_u32_e32 vcc, 0, v3
	s_and_saveexec_b64 s[8:9], vcc
	s_cbranch_execz .LBB0_466
	s_bcnt1_i32_b64 s10, s[10:11]
	s_lshl_b32 s10, s10, 1
	v_mov_b32_e32 v5, 0
	v_mov_b32_e32 v7, s10
	global_atomic_add v5, v5, v7, s[2:3] sc0
.LBB0_466:
	s_or_b64 exec, exec, s[8:9]
	s_mov_b64 s[8:9], exec
	s_waitcnt vmcnt(0)
	v_readfirstlane_b32 s15, v5
	v_mbcnt_lo_u32_b32 v5, s8, 0
	v_mbcnt_hi_u32_b32 v5, s9, v5
	v_cmp_eq_u32_e32 vcc, 0, v5
	s_and_saveexec_b64 s[10:11], vcc
	s_cbranch_execz .LBB0_468
	s_add_i32 s8, s15, 1
	v_mov_b32_e32 v7, s8

; DI void phase_attn(const Params& P, int l, LAS unsigned char* lds) {
;     ...
;     if (tid == 0) { const int a0 = (int)__hip_atomic_fetch_add(qctr, 1u, __ATOMIC_RELAXED, __HIP_MEMORY_SCOPE_AGENT); const int a1 = (int)__hip_atomic_fetch_add(qctr, 1u, __ATOMIC_RELAXED, __HIP_MEMORY_SCOPE_AGENT); slot[0] = a0; slot[1] = a1; }
.LBB0_1025:
	s_add_u32 s2, s50, 0x29e6f900
	s_addc_u32 s3, s51, 0
	v_cmp_eq_u32_e64 s[0:1], 0, v137
	s_and_saveexec_b64 s[4:5], s[0:1]
	s_cbranch_execz .LBB0_1031
	s_mov_b64 s[10:11], exec
	v_mbcnt_lo_u32_b32 v3, s10, 0
	v_mbcnt_hi_u32_b32 v3, s11, v3
	v_cmp_eq_u32_e32 vcc, 0, v3
	s_and_saveexec_b64 s[8:9], vcc
	s_cbranch_execz .LBB0_1028
	s_bcnt1_i32_b64 s10, s[10:11]
	s_lshl_b32 s10, s10, 1
	v_mov_b32_e32 v5, 0
	v_mov_b32_e32 v7, s10
	global_atomic_add v5, v5, v7, s[2:3] sc0
